# scan block reordered for ILP + hand-written lora_in
# speedup vs baseline: 1.0021x; 1.0021x over previous
; #define LAS __attribute__((address_space(3)))
; __device__ __forceinline__ float ksum(float p) { const f32x4 z = (f32x4){0.f, 0.f, 0.f, 0.f}; const f32x4 d = __builtin_amdgcn_mfma_f32_16x16x4f32(1.0f, p, z, 0, 0, 0); return d[0]; }
; #define RW_LD4(dst, P) do { _Pragma("unroll") for (int e = 0; e < 4; ++e) dst[e] = *(const LAS f32x4*)((P) + e * 16); } while (0)
; template <bool useB>
; __device__ __forceinline__ void rw_block4(ScanState& st, const LAS unsigned char* pb, const LAS float* pv, float* outA, float* outB, int kg) {
;     f32x4 oa[4], ob[4], ok[4], orr[2][4]; float ov;
;     ...
;     RW_LD4(oa, pb); RW_LD4(ob, pb + 256); RW_LD4(ok, pb + 512); RW_LD4(orr[0], pb + 768); ov = *pv;
;     float ykA = 0.f, ykB = 0.f;
;     const f32x4 z = (f32x4){0.f, 0.f, 0.f, 0.f};
; #pragma unroll
;     for (int ss = 0; ss < 4; ++ss) {
;         const bool more = ss < 3;
;         const LAS unsigned char* pn = pb + (ss + 1) * 1024; const LAS float* vn = pv + (ss + 1) * 16;
;         const float pa = dot16(st.A, oa), pq = useB ? dot16(st.B, oa) : 0.f;
;         const f32x4 da = __builtin_amdgcn_mfma_f32_16x16x4f32(1.0f, pa, z, 0, 0, 0);
;         f32x4 db = z; if (useB) db = __builtin_amdgcn_mfma_f32_16x16x4f32(1.0f, pq, z, 0, 0, 0);
;         if (more) RW_LD4(oa, pn);
;         if (ss > 0) { const float y = ksum(dot16(st.A, orr[(ss + 1) & 1])); ykA = (kg == ss - 1) ? y : ykA;
;             if (useB) { const float c = ksum(dot16(st.B, orr[(ss + 1) & 1])); ykB = (kg == ss - 1) ? c : ykB; } }
;         if (more) RW_LD4(orr[(ss + 1) & 1], pn + 768);
;         const float sa = da[0], sb = db[0];
;         const f32x4 sa4 = (f32x4){sa, sa, sa, sa}, sb4 = (f32x4){sb, sb, sb, sb}, v4 = (f32x4){ov, ov, ov, ov};
; #pragma unroll
;         for (int e = 0; e < 4; ++e) { st.A[e] = __builtin_elementwise_fma(ob[e], sa4, st.A[e]); st.A[e] = __builtin_elementwise_fma(ok[e], v4, st.A[e]); if (useB) st.B[e] = __builtin_elementwise_fma(ob[e], sb4, st.B[e]); }
;         if (more) { RW_LD4(ob, pn + 256); RW_LD4(ok, pn + 512); ov = *vn; }
.LBB0_1031:
	s_and_b32 s0, s51, 3
	v_lshl_add_u32 v85, s0, 12, v59
	v_lshl_add_u32 v111, s0, 8, v107
	ds_read_b128 v[128:131], v85
	ds_read_b128 v[132:135], v85 offset:16
	ds_read_b128 v[136:139], v85 offset:32
	ds_read_b128 v[140:143], v85 offset:48
	ds_read_b128 v[192:195], v85 offset:256
	ds_read_b128 v[196:199], v85 offset:272
	ds_read_b128 v[204:207], v85 offset:288
	ds_read_b128 v[208:211], v85 offset:304
	ds_read_b128 v[212:215], v85 offset:512
	ds_read_b128 v[216:219], v85 offset:528
	ds_read_b128 v[220:223], v85 offset:544
	ds_read_b128 v[224:227], v85 offset:560
	ds_read_b32 v16, v111
	s_waitcnt lgkmcnt(9)
	v_pk_mul_f32 v[248:249], v[36:37], v[128:129]
	v_pk_mul_f32 v[252:253], v[20:21], v[128:129]
	v_pk_mul_f32 v[250:251], v[38:39], v[130:131]
	v_pk_mul_f32 v[254:255], v[22:23], v[130:131]
	v_pk_fma_f32 v[248:249], v[40:41], v[132:133], v[248:249]
	v_pk_fma_f32 v[252:253], v[24:25], v[132:133], v[252:253]
	v_pk_fma_f32 v[250:251], v[42:43], v[134:135], v[250:251]
	v_pk_fma_f32 v[254:255], v[26:27], v[134:135], v[254:255]
	v_pk_fma_f32 v[248:249], v[48:49], v[136:137], v[248:249]
	v_pk_fma_f32 v[252:253], v[28:29], v[136:137], v[252:253]
	v_pk_fma_f32 v[250:251], v[50:51], v[138:139], v[250:251]
	v_pk_fma_f32 v[254:255], v[30:31], v[138:139], v[254:255]
	v_pk_fma_f32 v[248:249], v[44:45], v[140:141], v[248:249]
	v_pk_fma_f32 v[252:253], v[32:33], v[140:141], v[252:253]
	v_pk_fma_f32 v[250:251], v[46:47], v[142:143], v[250:251]
	v_pk_fma_f32 v[254:255], v[34:35], v[142:143], v[254:255]
	ds_read_b128 v[144:147], v85 offset:768
	ds_read_b128 v[148:151], v85 offset:784
	ds_read_b128 v[154:157], v85 offset:800
	ds_read_b128 v[158:161], v85 offset:816
	ds_read_b128 v[112:115], v85 offset:1024
	ds_read_b128 v[116:119], v85 offset:1040
	ds_read_b128 v[120:123], v85 offset:1056
	ds_read_b128 v[124:127], v85 offset:1072
	v_pk_add_f32 v[248:249], v[248:249], v[250:251]
	v_add_f32_e32 v2, v248, v249
	v_pk_add_f32 v[252:253], v[252:253], v[254:255]
	v_add_f32_e32 v18, v252, v253
	s_nop 0
	v_mfma_f32_16x16x4_f32 v[228:231], v61, v2, 0
	v_mfma_f32_16x16x4_f32 v[232:235], v61, v18, 0
	s_waitcnt lgkmcnt(0)
	s_nop 7
	v_pk_fma_f32 v[36:37], v[192:193], v[228:229], v[36:37] op_sel_hi:[1,0,1]
	v_pk_fma_f32 v[38:39], v[194:195], v[228:229], v[38:39] op_sel_hi:[1,0,1]
	v_pk_fma_f32 v[40:41], v[196:197], v[228:229], v[40:41] op_sel_hi:[1,0,1]
	v_pk_fma_f32 v[42:43], v[198:199], v[228:229], v[42:43] op_sel_hi:[1,0,1]
	v_pk_fma_f32 v[48:49], v[204:205], v[228:229], v[48:49] op_sel_hi:[1,0,1]
	v_pk_fma_f32 v[50:51], v[206:207], v[228:229], v[50:51] op_sel_hi:[1,0,1]
	v_pk_fma_f32 v[44:45], v[208:209], v[228:229], v[44:45] op_sel_hi:[1,0,1]
	v_pk_fma_f32 v[46:47], v[210:211], v[228:229], v[46:47] op_sel_hi:[1,0,1]
	v_pk_fma_f32 v[36:37], v[212:213], v[16:17], v[36:37] op_sel_hi:[1,0,1]
	v_pk_fma_f32 v[38:39], v[214:215], v[16:17], v[38:39] op_sel_hi:[1,0,1]
	v_pk_fma_f32 v[40:41], v[216:217], v[16:17], v[40:41] op_sel_hi:[1,0,1]
	v_pk_fma_f32 v[42:43], v[218:219], v[16:17], v[42:43] op_sel_hi:[1,0,1]
	v_pk_fma_f32 v[48:49], v[220:221], v[16:17], v[48:49] op_sel_hi:[1,0,1]
	v_pk_fma_f32 v[50:51], v[222:223], v[16:17], v[50:51] op_sel_hi:[1,0,1]
	v_pk_fma_f32 v[44:45], v[224:225], v[16:17], v[44:45] op_sel_hi:[1,0,1]
	v_pk_fma_f32 v[46:47], v[226:227], v[16:17], v[46:47] op_sel_hi:[1,0,1]
	v_pk_fma_f32 v[20:21], v[192:193], v[232:233], v[20:21] op_sel_hi:[1,0,1]
	v_pk_fma_f32 v[22:23], v[194:195], v[232:233], v[22:23] op_sel_hi:[1,0,1]
	v_pk_fma_f32 v[24:25], v[196:197], v[232:233], v[24:25] op_sel_hi:[1,0,1]
	v_pk_fma_f32 v[26:27], v[198:199], v[232:233], v[26:27] op_sel_hi:[1,0,1]
	v_pk_fma_f32 v[28:29], v[204:205], v[232:233], v[28:29] op_sel_hi:[1,0,1]
	v_pk_fma_f32 v[30:31], v[206:207], v[232:233], v[30:31] op_sel_hi:[1,0,1]
	v_pk_fma_f32 v[32:33], v[208:209], v[232:233], v[32:33] op_sel_hi:[1,0,1]
	v_pk_fma_f32 v[34:35], v[210:211], v[232:233], v[34:35] op_sel_hi:[1,0,1]
	ds_read_b128 v[192:195], v85 offset:1280
	ds_read_b128 v[196:199], v85 offset:1296
	ds_read_b128 v[204:207], v85 offset:1312
	ds_read_b128 v[208:211], v85 offset:1328
	ds_read_b128 v[212:215], v85 offset:1536
	ds_read_b128 v[216:219], v85 offset:1552
	ds_read_b128 v[220:223], v85 offset:1568
	ds_read_b128 v[224:227], v85 offset:1584
	ds_read_b32 v56, v111 offset:64
	ds_read_b128 v[168:171], v85 offset:1792
	ds_read_b128 v[172:175], v85 offset:1808
	ds_read_b128 v[184:187], v85 offset:1824
	ds_read_b128 v[188:191], v85 offset:1840
	ds_read_b128 v[128:131], v85 offset:2048
	ds_read_b128 v[132:135], v85 offset:2064
	ds_read_b128 v[136:139], v85 offset:2080
	ds_read_b128 v[140:143], v85 offset:2096
	v_pk_mul_f32 v[248:249], v[36:37], v[112:113]
	v_pk_mul_f32 v[252:253], v[20:21], v[112:113]
	v_pk_mul_f32 v[250:251], v[38:39], v[114:115]
	v_pk_mul_f32 v[254:255], v[22:23], v[114:115]
	v_pk_fma_f32 v[248:249], v[40:41], v[116:117], v[248:249]
	v_pk_fma_f32 v[252:253], v[24:25], v[116:117], v[252:253]
	v_pk_fma_f32 v[250:251], v[42:43], v[118:119], v[250:251]
	v_pk_fma_f32 v[254:255], v[26:27], v[118:119], v[254:255]
	v_pk_fma_f32 v[248:249], v[48:49], v[120:121], v[248:249]
	v_pk_fma_f32 v[252:253], v[28:29], v[120:121], v[252:253]
	v_pk_fma_f32 v[250:251], v[50:51], v[122:123], v[250:251]
	v_pk_fma_f32 v[254:255], v[30:31], v[122:123], v[254:255]
	v_pk_fma_f32 v[248:249], v[44:45], v[124:125], v[248:249]
	v_pk_fma_f32 v[252:253], v[32:33], v[124:125], v[252:253]
	v_pk_fma_f32 v[250:251], v[46:47], v[126:127], v[250:251]
	v_pk_fma_f32 v[254:255], v[34:35], v[126:127], v[254:255]
	v_pk_add_f32 v[248:249], v[248:249], v[250:251]
	v_pk_add_f32 v[252:253], v[252:253], v[254:255]
	v_add_f32_e32 v2, v248, v249
	v_add_f32_e32 v18, v252, v253
	v_pk_mul_f32 v[4:5], v[36:37], v[144:145]
	v_pk_mul_f32 v[8:9], v[20:21], v[144:145]
	v_mfma_f32_16x16x4_f32 v[228:231], v61, v2, 0
	v_pk_mul_f32 v[6:7], v[38:39], v[146:147]
	v_pk_mul_f32 v[10:11], v[22:23], v[146:147]
	v_mfma_f32_16x16x4_f32 v[232:235], v61, v18, 0
	v_pk_fma_f32 v[4:5], v[40:41], v[148:149], v[4:5]
	v_pk_fma_f32 v[8:9], v[24:25], v[148:149], v[8:9]
	v_pk_fma_f32 v[6:7], v[42:43], v[150:151], v[6:7]
	v_pk_fma_f32 v[10:11], v[26:27], v[150:151], v[10:11]
	v_pk_fma_f32 v[4:5], v[48:49], v[154:155], v[4:5]
	v_pk_fma_f32 v[8:9], v[28:29], v[154:155], v[8:9]
	v_pk_fma_f32 v[6:7], v[50:51], v[156:157], v[6:7]
	v_pk_fma_f32 v[10:11], v[30:31], v[156:157], v[10:11]
	v_pk_fma_f32 v[4:5], v[44:45], v[158:159], v[4:5]
	v_pk_fma_f32 v[8:9], v[32:33], v[158:159], v[8:9]
	v_pk_fma_f32 v[6:7], v[46:47], v[160:161], v[6:7]
	v_pk_fma_f32 v[10:11], v[34:35], v[160:161], v[10:11]
	v_pk_add_f32 v[4:5], v[4:5], v[6:7]
	v_pk_add_f32 v[8:9], v[8:9], v[10:11]
	v_add_f32_e32 v153, v4, v5
	v_add_f32_e32 v179, v8, v9
	s_nop 1
	v_mfma_f32_16x16x4_f32 v[236:239], v61, v153, 0
	v_mfma_f32_16x16x4_f32 v[244:247], v61, v179, 0
	s_waitcnt lgkmcnt(0)
; #define LAS __attribute__((address_space(3)))
; __device__ __forceinline__ float ksum(float p) { const f32x4 z = (f32x4){0.f, 0.f, 0.f, 0.f}; const f32x4 d = __builtin_amdgcn_mfma_f32_16x16x4f32(1.0f, p, z, 0, 0, 0); return d[0]; }
; #define RW_LD4(dst, P) do { _Pragma("unroll") for (int e = 0; e < 4; ++e) dst[e] = *(const LAS f32x4*)((P) + e * 16); } while (0)
; template <bool useB>
; __device__ __forceinline__ void rw_block4(ScanState& st, const LAS unsigned char* pb, const LAS float* pv, float* outA, float* outB, int kg) {
;     ...
;     for (int ss = 0; ss < 4; ++ss) {
;         const bool more = ss < 3;
;         const LAS unsigned char* pn = pb + (ss + 1) * 1024; const LAS float* vn = pv + (ss + 1) * 16;
;         const float pa = dot16(st.A, oa), pq = useB ? dot16(st.B, oa) : 0.f;
;         const f32x4 da = __builtin_amdgcn_mfma_f32_16x16x4f32(1.0f, pa, z, 0, 0, 0);
;         f32x4 db = z; if (useB) db = __builtin_amdgcn_mfma_f32_16x16x4f32(1.0f, pq, z, 0, 0, 0);
;         if (more) RW_LD4(oa, pn);
;         if (ss > 0) { const float y = ksum(dot16(st.A, orr[(ss + 1) & 1])); ykA = (kg == ss - 1) ? y : ykA;
;             if (useB) { const float c = ksum(dot16(st.B, orr[(ss + 1) & 1])); ykB = (kg == ss - 1) ? c : ykB; } }
;         if (more) RW_LD4(orr[(ss + 1) & 1], pn + 768);
;         const float sa = da[0], sb = db[0];
;         const f32x4 sa4 = (f32x4){sa, sa, sa, sa}, sb4 = (f32x4){sb, sb, sb, sb}, v4 = (f32x4){ov, ov, ov, ov};
; #pragma unroll
;         for (int e = 0; e < 4; ++e) { st.A[e] = __builtin_elementwise_fma(ob[e], sa4, st.A[e]); st.A[e] = __builtin_elementwise_fma(ok[e], v4, st.A[e]); if (useB) st.B[e] = __builtin_elementwise_fma(ob[e], sb4, st.B[e]); }
;         if (more) { RW_LD4(ob, pn + 256); RW_LD4(ok, pn + 512); ov = *vn; }
	v_pk_fma_f32 v[36:37], v[192:193], v[228:229], v[36:37] op_sel_hi:[1,0,1]
	v_pk_fma_f32 v[38:39], v[194:195], v[228:229], v[38:39] op_sel_hi:[1,0,1]
	v_pk_fma_f32 v[40:41], v[196:197], v[228:229], v[40:41] op_sel_hi:[1,0,1]
	v_pk_fma_f32 v[42:43], v[198:199], v[228:229], v[42:43] op_sel_hi:[1,0,1]
	v_pk_fma_f32 v[48:49], v[204:205], v[228:229], v[48:49] op_sel_hi:[1,0,1]
	v_pk_fma_f32 v[50:51], v[206:207], v[228:229], v[50:51] op_sel_hi:[1,0,1]
	v_pk_fma_f32 v[44:45], v[208:209], v[228:229], v[44:45] op_sel_hi:[1,0,1]
	v_pk_fma_f32 v[46:47], v[210:211], v[228:229], v[46:47] op_sel_hi:[1,0,1]
	v_pk_fma_f32 v[36:37], v[212:213], v[56:57], v[36:37] op_sel_hi:[1,0,1]
	v_pk_fma_f32 v[38:39], v[214:215], v[56:57], v[38:39] op_sel_hi:[1,0,1]
	v_pk_fma_f32 v[40:41], v[216:217], v[56:57], v[40:41] op_sel_hi:[1,0,1]
	v_pk_fma_f32 v[42:43], v[218:219], v[56:57], v[42:43] op_sel_hi:[1,0,1]
	v_pk_fma_f32 v[48:49], v[220:221], v[56:57], v[48:49] op_sel_hi:[1,0,1]
	v_pk_fma_f32 v[50:51], v[222:223], v[56:57], v[50:51] op_sel_hi:[1,0,1]
	v_pk_fma_f32 v[44:45], v[224:225], v[56:57], v[44:45] op_sel_hi:[1,0,1]
	v_pk_fma_f32 v[46:47], v[226:227], v[56:57], v[46:47] op_sel_hi:[1,0,1]
	v_cndmask_b32_e64 v203, 0, v236, s[8:9]
	v_cndmask_b32_e64 v241, 0, v244, s[8:9]
	v_pk_fma_f32 v[20:21], v[192:193], v[232:233], v[20:21] op_sel_hi:[1,0,1]
	v_pk_fma_f32 v[22:23], v[194:195], v[232:233], v[22:23] op_sel_hi:[1,0,1]
	v_pk_fma_f32 v[24:25], v[196:197], v[232:233], v[24:25] op_sel_hi:[1,0,1]
	v_pk_fma_f32 v[26:27], v[198:199], v[232:233], v[26:27] op_sel_hi:[1,0,1]
	v_pk_fma_f32 v[28:29], v[204:205], v[232:233], v[28:29] op_sel_hi:[1,0,1]
	v_pk_fma_f32 v[30:31], v[206:207], v[232:233], v[30:31] op_sel_hi:[1,0,1]
	v_pk_fma_f32 v[32:33], v[208:209], v[232:233], v[32:33] op_sel_hi:[1,0,1]
	v_pk_fma_f32 v[34:35], v[210:211], v[232:233], v[34:35] op_sel_hi:[1,0,1]
	ds_read_b128 v[192:195], v85 offset:2304
	ds_read_b128 v[196:199], v85 offset:2320
	ds_read_b128 v[204:207], v85 offset:2336
	ds_read_b128 v[208:211], v85 offset:2352
	ds_read_b128 v[212:215], v85 offset:2560
	ds_read_b128 v[216:219], v85 offset:2576
	ds_read_b128 v[220:223], v85 offset:2592
	ds_read_b128 v[224:227], v85 offset:2608
	ds_read_b32 v16, v111 offset:128
	ds_read_b128 v[144:147], v85 offset:2816
	ds_read_b128 v[148:151], v85 offset:2832
	ds_read_b128 v[154:157], v85 offset:2848
	ds_read_b128 v[158:161], v85 offset:2864
	ds_read_b128 v[112:115], v85 offset:3072
	ds_read_b128 v[116:119], v85 offset:3088
	ds_read_b128 v[120:123], v85 offset:3104
	ds_read_b128 v[124:127], v85 offset:3120
	v_pk_mul_f32 v[248:249], v[36:37], v[128:129]
	v_pk_mul_f32 v[252:253], v[20:21], v[128:129]
	v_pk_mul_f32 v[250:251], v[38:39], v[130:131]
	v_pk_mul_f32 v[254:255], v[22:23], v[130:131]
	v_pk_fma_f32 v[248:249], v[40:41], v[132:133], v[248:249]
	v_pk_fma_f32 v[252:253], v[24:25], v[132:133], v[252:253]
	v_pk_fma_f32 v[250:251], v[42:43], v[134:135], v[250:251]
	v_pk_fma_f32 v[254:255], v[26:27], v[134:135], v[254:255]
	v_pk_fma_f32 v[248:249], v[48:49], v[136:137], v[248:249]
	v_pk_fma_f32 v[252:253], v[28:29], v[136:137], v[252:253]
	v_pk_fma_f32 v[250:251], v[50:51], v[138:139], v[250:251]
	v_pk_fma_f32 v[254:255], v[30:31], v[138:139], v[254:255]
	v_pk_fma_f32 v[248:249], v[44:45], v[140:141], v[248:249]
	v_pk_fma_f32 v[252:253], v[32:33], v[140:141], v[252:253]
	v_pk_fma_f32 v[250:251], v[46:47], v[142:143], v[250:251]
	v_pk_fma_f32 v[254:255], v[34:35], v[142:143], v[254:255]
	v_pk_add_f32 v[248:249], v[248:249], v[250:251]
	v_pk_add_f32 v[252:253], v[252:253], v[254:255]
	v_add_f32_e32 v2, v248, v249
	v_add_f32_e32 v18, v252, v253
	v_pk_mul_f32 v[4:5], v[36:37], v[168:169]
	v_pk_mul_f32 v[8:9], v[20:21], v[168:169]
	v_mfma_f32_16x16x4_f32 v[228:231], v61, v2, 0
	v_pk_mul_f32 v[6:7], v[38:39], v[170:171]
	v_pk_mul_f32 v[10:11], v[22:23], v[170:171]
	v_mfma_f32_16x16x4_f32 v[232:235], v61, v18, 0
	v_pk_fma_f32 v[4:5], v[40:41], v[172:173], v[4:5]
	v_pk_fma_f32 v[8:9], v[24:25], v[172:173], v[8:9]
	v_pk_fma_f32 v[6:7], v[42:43], v[174:175], v[6:7]
	v_pk_fma_f32 v[10:11], v[26:27], v[174:175], v[10:11]
	v_pk_fma_f32 v[4:5], v[48:49], v[184:185], v[4:5]
	v_pk_fma_f32 v[8:9], v[28:29], v[184:185], v[8:9]
	v_pk_fma_f32 v[6:7], v[50:51], v[186:187], v[6:7]
	v_pk_fma_f32 v[10:11], v[30:31], v[186:187], v[10:11]
	v_pk_fma_f32 v[4:5], v[44:45], v[188:189], v[4:5]
	v_pk_fma_f32 v[8:9], v[32:33], v[188:189], v[8:9]
	v_pk_fma_f32 v[6:7], v[46:47], v[190:191], v[6:7]
	v_pk_fma_f32 v[10:11], v[34:35], v[190:191], v[10:11]
	v_pk_add_f32 v[4:5], v[4:5], v[6:7]
	v_pk_add_f32 v[8:9], v[8:9], v[10:11]
	v_add_f32_e32 v153, v4, v5
	v_add_f32_e32 v179, v8, v9
	s_nop 1
	v_mfma_f32_16x16x4_f32 v[236:239], v61, v153, 0
	v_mfma_f32_16x16x4_f32 v[244:247], v61, v179, 0
	s_waitcnt lgkmcnt(0)
; #define LAS __attribute__((address_space(3)))
; __device__ __forceinline__ float ksum(float p) { const f32x4 z = (f32x4){0.f, 0.f, 0.f, 0.f}; const f32x4 d = __builtin_amdgcn_mfma_f32_16x16x4f32(1.0f, p, z, 0, 0, 0); return d[0]; }
; #define RW_LD4(dst, P) do { _Pragma("unroll") for (int e = 0; e < 4; ++e) dst[e] = *(const LAS f32x4*)((P) + e * 16); } while (0)
; template <bool useB>
; __device__ __forceinline__ void rw_block4(ScanState& st, const LAS unsigned char* pb, const LAS float* pv, float* outA, float* outB, int kg) {
;     ...
;     for (int ss = 0; ss < 4; ++ss) {
;         const bool more = ss < 3;
;         const LAS unsigned char* pn = pb + (ss + 1) * 1024; const LAS float* vn = pv + (ss + 1) * 16;
;         const float pa = dot16(st.A, oa), pq = useB ? dot16(st.B, oa) : 0.f;
;         const f32x4 da = __builtin_amdgcn_mfma_f32_16x16x4f32(1.0f, pa, z, 0, 0, 0);
;         f32x4 db = z; if (useB) db = __builtin_amdgcn_mfma_f32_16x16x4f32(1.0f, pq, z, 0, 0, 0);
;         if (more) RW_LD4(oa, pn);
;         if (ss > 0) { const float y = ksum(dot16(st.A, orr[(ss + 1) & 1])); ykA = (kg == ss - 1) ? y : ykA;
;             if (useB) { const float c = ksum(dot16(st.B, orr[(ss + 1) & 1])); ykB = (kg == ss - 1) ? c : ykB; } }
;         if (more) RW_LD4(orr[(ss + 1) & 1], pn + 768);
;         const float sa = da[0], sb = db[0];
;         const f32x4 sa4 = (f32x4){sa, sa, sa, sa}, sb4 = (f32x4){sb, sb, sb, sb}, v4 = (f32x4){ov, ov, ov, ov};
; #pragma unroll
;         for (int e = 0; e < 4; ++e) { st.A[e] = __builtin_elementwise_fma(ob[e], sa4, st.A[e]); st.A[e] = __builtin_elementwise_fma(ok[e], v4, st.A[e]); if (useB) st.B[e] = __builtin_elementwise_fma(ob[e], sb4, st.B[e]); }
;         if (more) { RW_LD4(ob, pn + 256); RW_LD4(ok, pn + 512); ov = *vn; }
	v_pk_fma_f32 v[36:37], v[192:193], v[228:229], v[36:37] op_sel_hi:[1,0,1]
	v_pk_fma_f32 v[38:39], v[194:195], v[228:229], v[38:39] op_sel_hi:[1,0,1]
	v_pk_fma_f32 v[40:41], v[196:197], v[228:229], v[40:41] op_sel_hi:[1,0,1]
	v_pk_fma_f32 v[42:43], v[198:199], v[228:229], v[42:43] op_sel_hi:[1,0,1]
	v_pk_fma_f32 v[48:49], v[204:205], v[228:229], v[48:49] op_sel_hi:[1,0,1]
	v_pk_fma_f32 v[50:51], v[206:207], v[228:229], v[50:51] op_sel_hi:[1,0,1]
	v_pk_fma_f32 v[44:45], v[208:209], v[228:229], v[44:45] op_sel_hi:[1,0,1]
	v_pk_fma_f32 v[46:47], v[210:211], v[228:229], v[46:47] op_sel_hi:[1,0,1]
	v_pk_fma_f32 v[36:37], v[212:213], v[16:17], v[36:37] op_sel_hi:[1,0,1]
	v_pk_fma_f32 v[38:39], v[214:215], v[16:17], v[38:39] op_sel_hi:[1,0,1]
	v_pk_fma_f32 v[40:41], v[216:217], v[16:17], v[40:41] op_sel_hi:[1,0,1]
	v_pk_fma_f32 v[42:43], v[218:219], v[16:17], v[42:43] op_sel_hi:[1,0,1]
	v_pk_fma_f32 v[48:49], v[220:221], v[16:17], v[48:49] op_sel_hi:[1,0,1]
	v_pk_fma_f32 v[50:51], v[222:223], v[16:17], v[50:51] op_sel_hi:[1,0,1]
	v_pk_fma_f32 v[44:45], v[224:225], v[16:17], v[44:45] op_sel_hi:[1,0,1]
	v_pk_fma_f32 v[46:47], v[226:227], v[16:17], v[46:47] op_sel_hi:[1,0,1]
	v_cndmask_b32_e64 v203, v203, v236, s[12:13]
	v_cndmask_b32_e64 v241, v241, v244, s[12:13]
	v_pk_fma_f32 v[20:21], v[192:193], v[232:233], v[20:21] op_sel_hi:[1,0,1]
	v_pk_fma_f32 v[22:23], v[194:195], v[232:233], v[22:23] op_sel_hi:[1,0,1]
	v_pk_fma_f32 v[24:25], v[196:197], v[232:233], v[24:25] op_sel_hi:[1,0,1]
	v_pk_fma_f32 v[26:27], v[198:199], v[232:233], v[26:27] op_sel_hi:[1,0,1]
	v_pk_fma_f32 v[28:29], v[204:205], v[232:233], v[28:29] op_sel_hi:[1,0,1]
	v_pk_fma_f32 v[30:31], v[206:207], v[232:233], v[30:31] op_sel_hi:[1,0,1]
	v_pk_fma_f32 v[32:33], v[208:209], v[232:233], v[32:33] op_sel_hi:[1,0,1]
	v_pk_fma_f32 v[34:35], v[210:211], v[232:233], v[34:35] op_sel_hi:[1,0,1]
	ds_read_b128 v[192:195], v85 offset:3328
	ds_read_b128 v[196:199], v85 offset:3344
	ds_read_b128 v[204:207], v85 offset:3360
	ds_read_b128 v[208:211], v85 offset:3376
	ds_read_b128 v[212:215], v85 offset:3584
	ds_read_b128 v[216:219], v85 offset:3600
	ds_read_b128 v[220:223], v85 offset:3616
	ds_read_b128 v[224:227], v85 offset:3632
	ds_read_b32 v56, v111 offset:192
	ds_read_b128 v[168:171], v85 offset:3840
	ds_read_b128 v[172:175], v85 offset:3856
	ds_read_b128 v[184:187], v85 offset:3872
	ds_read_b128 v[188:191], v85 offset:3888
	v_pk_mul_f32 v[248:249], v[36:37], v[112:113]
	v_pk_mul_f32 v[252:253], v[20:21], v[112:113]
	v_pk_mul_f32 v[250:251], v[38:39], v[114:115]
	v_pk_mul_f32 v[254:255], v[22:23], v[114:115]
	v_pk_fma_f32 v[248:249], v[40:41], v[116:117], v[248:249]
	v_pk_fma_f32 v[252:253], v[24:25], v[116:117], v[252:253]
	v_pk_fma_f32 v[250:251], v[42:43], v[118:119], v[250:251]
	v_pk_fma_f32 v[254:255], v[26:27], v[118:119], v[254:255]
	v_pk_fma_f32 v[248:249], v[48:49], v[120:121], v[248:249]
	v_pk_fma_f32 v[252:253], v[28:29], v[120:121], v[252:253]
	v_pk_fma_f32 v[250:251], v[50:51], v[122:123], v[250:251]
	v_pk_fma_f32 v[254:255], v[30:31], v[122:123], v[254:255]
	v_pk_fma_f32 v[248:249], v[44:45], v[124:125], v[248:249]
	v_pk_fma_f32 v[252:253], v[32:33], v[124:125], v[252:253]
	v_pk_fma_f32 v[250:251], v[46:47], v[126:127], v[250:251]
	v_pk_fma_f32 v[254:255], v[34:35], v[126:127], v[254:255]
	v_pk_add_f32 v[248:249], v[248:249], v[250:251]
	v_pk_add_f32 v[252:253], v[252:253], v[254:255]
	v_add_f32_e32 v2, v248, v249
	v_add_f32_e32 v18, v252, v253
	v_pk_mul_f32 v[4:5], v[36:37], v[144:145]
	v_pk_mul_f32 v[8:9], v[20:21], v[144:145]
	v_mfma_f32_16x16x4_f32 v[228:231], v61, v2, 0
	v_pk_mul_f32 v[6:7], v[38:39], v[146:147]
	v_pk_mul_f32 v[10:11], v[22:23], v[146:147]
	v_mfma_f32_16x16x4_f32 v[232:235], v61, v18, 0
	v_pk_fma_f32 v[4:5], v[40:41], v[148:149], v[4:5]
	v_pk_fma_f32 v[8:9], v[24:25], v[148:149], v[8:9]
	v_pk_fma_f32 v[6:7], v[42:43], v[150:151], v[6:7]
	v_pk_fma_f32 v[10:11], v[26:27], v[150:151], v[10:11]
	v_pk_fma_f32 v[4:5], v[48:49], v[154:155], v[4:5]
	v_pk_fma_f32 v[8:9], v[28:29], v[154:155], v[8:9]
	v_pk_fma_f32 v[6:7], v[50:51], v[156:157], v[6:7]
	v_pk_fma_f32 v[10:11], v[30:31], v[156:157], v[10:11]
	v_pk_fma_f32 v[4:5], v[44:45], v[158:159], v[4:5]
	v_pk_fma_f32 v[8:9], v[32:33], v[158:159], v[8:9]
	v_pk_fma_f32 v[6:7], v[46:47], v[160:161], v[6:7]
	v_pk_fma_f32 v[10:11], v[34:35], v[160:161], v[10:11]
	v_pk_add_f32 v[4:5], v[4:5], v[6:7]
	v_pk_add_f32 v[8:9], v[8:9], v[10:11]
	v_add_f32_e32 v153, v4, v5
	v_add_f32_e32 v179, v8, v9
	s_nop 1
	v_mfma_f32_16x16x4_f32 v[236:239], v61, v153, 0
	v_mfma_f32_16x16x4_f32 v[244:247], v61, v179, 0
	s_waitcnt lgkmcnt(0)
; #define LAS __attribute__((address_space(3)))
; template <bool useB>
; __device__ __forceinline__ void rw_block4(ScanState& st, const LAS unsigned char* pb, const LAS float* pv, float* outA, float* outB, int kg) {
;     ...
;         if (ss > 0) { const float y = ksum(dot16(st.A, orr[(ss + 1) & 1])); ykA = (kg == ss - 1) ? y : ykA;
;             if (useB) { const float c = ksum(dot16(st.B, orr[(ss + 1) & 1])); ykB = (kg == ss - 1) ? c : ykB; } }
;         if (more) RW_LD4(orr[(ss + 1) & 1], pn + 768);
;         const float sa = da[0], sb = db[0];
;         const f32x4 sa4 = (f32x4){sa, sa, sa, sa}, sb4 = (f32x4){sb, sb, sb, sb}, v4 = (f32x4){ov, ov, ov, ov};
; #pragma unroll
;         for (int e = 0; e < 4; ++e) { st.A[e] = __builtin_elementwise_fma(ob[e], sa4, st.A[e]); st.A[e] = __builtin_elementwise_fma(ok[e], v4, st.A[e]); if (useB) st.B[e] = __builtin_elementwise_fma(ob[e], sb4, st.B[e]); }
;         if (more) { RW_LD4(ob, pn + 256); RW_LD4(ok, pn + 512); ov = *vn; }
;     }
;     { const float y = ksum(dot16(st.A, orr[1])); ykA = (kg == 3) ? y : ykA; outA[(size_t)kg * DH] = ykA;
;       if (useB) { const float c = ksum(dot16(st.B, orr[1])); ykB = (kg == 3) ? c : ykB; outB[(size_t)kg * DH] = ykB; } }
;     ...
; }
; __device__ __forceinline__ void rw_issue(Frame& F, int w, int k, int rec, const float* vrow0, const float* wcp, int par, int lane) {
;     const float* REC = (const float*)(F.ws + WS_REC);
;     LAS unsigned char* dst = F.lds + w * 16384 + k * 4096;
;     const unsigned* gp = (const unsigned*)(REC + (size_t)rec * 256 + lane * 4); LAS unsigned* lp = (LAS unsigned*)dst;
;     __builtin_amdgcn_global_load_lds(gp, lp, 16, 0, 0); __builtin_amdgcn_global_load_lds(gp, lp, 16, 1024, 0); __builtin_amdgcn_global_load_lds(gp, lp, 16, 2048, 0); __builtin_amdgcn_global_load_lds(gp, lp, 16, 3072, 0);
;     __builtin_amdgcn_global_load_lds((const unsigned*)(vrow0 + (size_t)(lane >> 4) * DH + (lane & 15)), (LAS unsigned*)(F.lds + 131072 + w * 1024 + k * 256), 4, 0, 0);
;     __builtin_amdgcn_global_load_lds((const unsigned*)(wcp + lane), (LAS unsigned*)(F.lds + 139264 + w * 512 + par * 256), 4, 0, 0);
; }
; template <bool useB>
; __device__ __forceinline__ void rw_job(Frame& F, ScanState& st, int rec0, const float* vrow0, const float* wcp0, int nsteps, float* outA0, float* outB0, int w, int lane) {
;     const int r = lane & 15, kg = lane >> 4; const int nb = nsteps / TB;
	v_pk_fma_f32 v[36:37], v[192:193], v[228:229], v[36:37] op_sel_hi:[1,0,1]
	v_pk_fma_f32 v[38:39], v[194:195], v[228:229], v[38:39] op_sel_hi:[1,0,1]
	v_pk_fma_f32 v[40:41], v[196:197], v[228:229], v[40:41] op_sel_hi:[1,0,1]
	v_pk_fma_f32 v[42:43], v[198:199], v[228:229], v[42:43] op_sel_hi:[1,0,1]
	v_pk_fma_f32 v[48:49], v[204:205], v[228:229], v[48:49] op_sel_hi:[1,0,1]
	v_pk_fma_f32 v[50:51], v[206:207], v[228:229], v[50:51] op_sel_hi:[1,0,1]
	v_pk_fma_f32 v[44:45], v[208:209], v[228:229], v[44:45] op_sel_hi:[1,0,1]
	v_pk_fma_f32 v[46:47], v[210:211], v[228:229], v[46:47] op_sel_hi:[1,0,1]
	v_pk_fma_f32 v[36:37], v[212:213], v[56:57], v[36:37] op_sel_hi:[1,0,1]
	v_pk_fma_f32 v[38:39], v[214:215], v[56:57], v[38:39] op_sel_hi:[1,0,1]
	v_pk_fma_f32 v[40:41], v[216:217], v[56:57], v[40:41] op_sel_hi:[1,0,1]
	v_pk_fma_f32 v[42:43], v[218:219], v[56:57], v[42:43] op_sel_hi:[1,0,1]
	v_pk_fma_f32 v[48:49], v[220:221], v[56:57], v[48:49] op_sel_hi:[1,0,1]
	v_pk_fma_f32 v[50:51], v[222:223], v[56:57], v[50:51] op_sel_hi:[1,0,1]
	v_pk_fma_f32 v[44:45], v[224:225], v[56:57], v[44:45] op_sel_hi:[1,0,1]
	v_pk_fma_f32 v[46:47], v[226:227], v[56:57], v[46:47] op_sel_hi:[1,0,1]
	v_cndmask_b32_e64 v203, v203, v236, s[10:11]
	v_cndmask_b32_e64 v241, v241, v244, s[10:11]
	v_pk_fma_f32 v[20:21], v[192:193], v[232:233], v[20:21] op_sel_hi:[1,0,1]
	v_pk_fma_f32 v[22:23], v[194:195], v[232:233], v[22:23] op_sel_hi:[1,0,1]
	v_pk_fma_f32 v[24:25], v[196:197], v[232:233], v[24:25] op_sel_hi:[1,0,1]
	v_pk_fma_f32 v[26:27], v[198:199], v[232:233], v[26:27] op_sel_hi:[1,0,1]
	v_pk_fma_f32 v[28:29], v[204:205], v[232:233], v[28:29] op_sel_hi:[1,0,1]
	v_pk_fma_f32 v[30:31], v[206:207], v[232:233], v[30:31] op_sel_hi:[1,0,1]
	v_pk_fma_f32 v[32:33], v[208:209], v[232:233], v[32:33] op_sel_hi:[1,0,1]
	v_pk_fma_f32 v[34:35], v[210:211], v[232:233], v[34:35] op_sel_hi:[1,0,1]
	v_pk_mul_f32 v[4:5], v[36:37], v[168:169]
	v_pk_mul_f32 v[6:7], v[38:39], v[170:171]
	v_pk_fma_f32 v[4:5], v[40:41], v[172:173], v[4:5]
	v_pk_fma_f32 v[6:7], v[42:43], v[174:175], v[6:7]
	v_pk_fma_f32 v[4:5], v[48:49], v[184:185], v[4:5]
	v_pk_fma_f32 v[6:7], v[50:51], v[186:187], v[6:7]
	v_pk_fma_f32 v[4:5], v[44:45], v[188:189], v[4:5]
	v_pk_fma_f32 v[6:7], v[46:47], v[190:191], v[6:7]
	v_pk_add_f32 v[4:5], v[4:5], v[6:7]
	v_add_f32_e32 v153, v4, v5
	v_pk_mul_f32 v[8:9], v[20:21], v[168:169]
	v_pk_mul_f32 v[10:11], v[22:23], v[170:171]
	v_mfma_f32_16x16x4_f32 v[236:239], v61, v153, 0
	v_pk_fma_f32 v[8:9], v[24:25], v[172:173], v[8:9]
	v_pk_fma_f32 v[10:11], v[26:27], v[174:175], v[10:11]
	v_pk_fma_f32 v[8:9], v[28:29], v[184:185], v[8:9]
	v_pk_fma_f32 v[10:11], v[30:31], v[186:187], v[10:11]
	v_pk_fma_f32 v[8:9], v[32:33], v[188:189], v[8:9]
	v_pk_fma_f32 v[10:11], v[34:35], v[190:191], v[10:11]
	v_pk_add_f32 v[8:9], v[8:9], v[10:11]
	v_add_f32_e32 v179, v8, v9
	v_lshl_add_u64 v[12:13], v[90:91], 0, s[24:25]
	v_lshl_add_u64 v[14:15], v[92:93], 0, s[24:25]
	v_mfma_f32_16x16x4_f32 v[244:247], v61, v179, 0
	s_nop 9
	v_cndmask_b32_e64 v203, v203, v236, s[14:15]
	v_cndmask_b32_e64 v241, v241, v244, s[14:15]
	global_store_dword v[12:13], v203, off
	global_store_dword v[14:15], v241, off
	s_and_b32 s0, s51, 15
	s_cmp_lg_u32 s0, 15
	s_cbranch_scc1 .LBB0_1026
	s_and_b32 s0, s50, 0x100
	v_add_u32_e32 v52, s0, v108
	v_add_u32_e32 v56, s0, v109
	ds_read_b128 v[52:55], v52
	v_add_u32_e32 v57, 0x22010, v56
	ds_read_b128 v[112:115], v57
	s_waitcnt lgkmcnt(0)
	v_pk_mul_f32 v[36:37], v[36:37], v[52:53]
	v_pk_mul_f32 v[20:21], v[20:21], v[52:53]
	v_add_u32_e32 v52, 0x22020, v56
	v_add_u32_e32 v56, 0x22030, v56
	v_pk_mul_f32 v[38:39], v[38:39], v[54:55]
	v_pk_mul_f32 v[22:23], v[22:23], v[54:55]
	v_pk_mul_f32 v[42:43], v[42:43], v[114:115]
	v_pk_mul_f32 v[40:41], v[40:41], v[112:113]
	ds_read_b128 v[52:55], v52
	v_pk_mul_f32 v[26:27], v[26:27], v[114:115]
	v_pk_mul_f32 v[24:25], v[24:25], v[112:113]
	ds_read_b128 v[112:115], v56
	s_waitcnt lgkmcnt(0)
	v_pk_mul_f32 v[50:51], v[50:51], v[54:55]
	v_pk_mul_f32 v[48:49], v[48:49], v[52:53]
	v_pk_mul_f32 v[30:31], v[30:31], v[54:55]
	v_pk_mul_f32 v[28:29], v[28:29], v[52:53]
	v_pk_mul_f32 v[46:47], v[46:47], v[114:115]
	v_pk_mul_f32 v[44:45], v[44:45], v[112:113]
	v_pk_mul_f32 v[34:35], v[34:35], v[114:115]
	v_pk_mul_f32 v[32:33], v[32:33], v[112:113]
	s_branch .LBB0_1026
